# attention tile loop: K/V tiles staged by LDS-DMA (global_load_lds) instead of VGPR staging + ds_write, one barrier per tile, softmax-finish before QK
# baseline (speedup 1.0000x reference)
.LBB0_558:
	v_ashrrev_i32_e32 v179, 4, v166
	s_waitcnt vmcnt(7)
	v_and_b32_e32 v4, 0xfffff0, v179
	v_lshlrev_b32_e32 v5, 1, v179
	v_lshlrev_b32_e32 v2, 3, v166
	v_and_or_b32 v4, v5, 8, v4
	v_and_b32_e32 v3, 0x78, v2
	v_lshrrev_b32_e32 v5, 1, v179
	v_lshrrev_b32_e32 v4, 1, v4
	v_bfe_u32 v2, v2, 5, 2
	s_waitcnt vmcnt(6)
	v_and_b32_e32 v6, 3, v179
	v_or_b32_e32 v4, v4, v2
	v_and_or_b32 v5, v5, 4, v6
	v_lshlrev_b32_e32 v130, 1, v3
	v_lshlrev_b32_e32 v4, 9, v4
	v_lshlrev_b32_e32 v5, 6, v5
	v_and_b32_e32 v3, 48, v130
	v_add_u32_e32 v181, 32, v179
	s_waitcnt vmcnt(3)
	v_or3_b32 v18, v4, v5, v3
	v_and_b32_e32 v4, 0xfffff0, v181
	v_lshlrev_b32_e32 v6, 1, v181
	v_and_or_b32 v4, v6, 8, v4
	v_lshrrev_b32_e32 v4, 1, v4
	v_or_b32_e32 v2, v4, v2
	v_and_b32_e32 v165, 63, v166
	v_lshlrev_b32_e32 v2, 9, v2
	v_or3_b32 v19, v2, v5, v3
	v_lshlrev_b32_e32 v3, 4, v165
	s_and_b32 s0, s40, 0x3fffffc0
	v_lshlrev_b32_e32 v2, 3, v165
	v_and_b32_e32 v3, 0xc0, v3
	v_lshlrev_b32_e32 v4, 1, v165
	s_lshl_b32 s0, s0, 2
	v_and_or_b32 v3, v2, 24, v3
	v_and_b32_e32 v4, 32, v4
	v_and_b32_e32 v2, 0x100, v2
	s_add_i32 s70, s0, 0
	v_or3_b32 v171, v3, v4, v2
	v_mad_i64_i32 v[2:3], s[0:1], s28, v179, 0
	v_lshlrev_b64 v[34:35], 1, v[2:3]
	v_lshl_add_u64 v[2:3], s[50:51], 0, v[34:35]
	v_lshl_add_u64 v[2:3], v[2:3], 0, v[130:131]
	global_load_dwordx4 v[2:5], v[2:3], off
	v_mad_i64_i32 v[6:7], s[0:1], s28, v181, 0
	v_lshlrev_b64 v[36:37], 1, v[6:7]
	v_lshl_add_u64 v[6:7], s[50:51], 0, v[36:37]
	v_lshl_add_u64 v[10:11], s[96:97], 0, v[34:35]
	v_lshl_add_u64 v[14:15], s[96:97], 0, v[36:37]
	v_lshl_add_u64 v[6:7], v[6:7], 0, v[130:131]
	v_lshl_add_u64 v[10:11], v[10:11], 0, v[130:131]
	v_lshl_add_u64 v[14:15], v[14:15], 0, v[130:131]
	global_load_dwordx4 v[6:9], v[6:7], off
	v_add_u32_e32 v187, 0, v18
	global_load_dwordx4 v[10:13], v[10:11], off
	v_add_u32_e32 v188, 0, v19
	global_load_dwordx4 v[14:17], v[14:15], off
	s_waitcnt vmcnt(0)
	s_movk_i32 s0, 0x70
	v_lshl_add_u32 v47, v167, 8, 0
	s_add_i32 s70, s70, 0x10000
	v_add_u32_e32 v176, 0, v171
	v_lshl_add_u32 v177, v167, 2, s70
	s_waitcnt vmcnt(3)
	ds_write_b128 v187, v[2:5]
	v_lshlrev_b32_e32 v2, 8, v179
	v_and_b32_e32 v3, 0x70, v166
	v_bitop3_b32 v2, v130, v2, v3 bitop3:0xde
	v_add_u32_e32 v191, 0, v2
	v_lshlrev_b32_e32 v2, 8, v181
	v_bitop3_b32 v2, v130, v2, v3 bitop3:0xde
	v_add_u32_e32 v192, 0, v2
	v_lshlrev_b32_e32 v2, 4, v167
	v_and_b32_e32 v46, 0x70, v2
	s_waitcnt vmcnt(2)
	ds_write_b128 v188, v[6:9]
	v_bitop3_b32 v2, v164, v2, s0 bitop3:0x78
	s_waitcnt vmcnt(1)
	ds_write_b128 v191, v[10:13] offset:32768
	v_add_u32_e32 v180, v47, v2
	s_waitcnt vmcnt(0)
	ds_write_b128 v192, v[14:17] offset:32768
	s_waitcnt lgkmcnt(0)
	s_barrier
	ds_read_b128 v[2:5], v180 offset:32768
	ds_read_b128 v[6:9], v180 offset:40960
	s_waitcnt lgkmcnt(1)
	v_mfma_f32_32x32x16_bf16 v[18:33], v[2:5], v[136:139], 0
	v_bitop3_b32 v38, v164, v46, 32 bitop3:0x36
	v_add_u32_e32 v182, v47, v38
	ds_read_b128 v[38:41], v182 offset:32768
	ds_read_b128 v[42:45], v182 offset:40960
	s_movk_i32 s0, 0x60
	s_waitcnt lgkmcnt(2)
	v_mfma_f32_32x32x16_bf16 v[2:17], v[6:9], v[136:139], 0
	s_waitcnt lgkmcnt(1)
	v_mfma_f32_32x32x16_bf16 v[18:33], v[38:41], v[144:147], v[18:33]
	v_bitop3_b32 v38, v164, v46, 64 bitop3:0x36
	v_add_u32_e32 v183, v47, v38
	s_waitcnt lgkmcnt(0)
	v_mfma_f32_32x32x16_bf16 v[2:17], v[42:45], v[144:147], v[2:17]
	ds_read_b128 v[38:41], v183 offset:32768
	ds_read_b128 v[42:45], v183 offset:40960
	s_waitcnt lgkmcnt(1)
	v_mfma_f32_32x32x16_bf16 v[18:33], v[38:41], v[132:135], v[18:33]
	v_bitop3_b32 v38, v164, v46, s0 bitop3:0x36
	v_add_u32_e32 v184, v47, v38
	s_movk_i32 s0, 0x80
	s_waitcnt lgkmcnt(0)
	v_mfma_f32_32x32x16_bf16 v[2:17], v[42:45], v[132:135], v[2:17]
	ds_read_b128 v[38:41], v184 offset:32768
	ds_read_b128 v[42:45], v184 offset:40960
	s_waitcnt lgkmcnt(1)
	v_mfma_f32_32x32x16_bf16 v[18:33], v[38:41], v[140:143], v[18:33]
	v_bitop3_b32 v38, v164, v46, s0 bitop3:0x36
	v_add_u32_e32 v185, v47, v38
	s_movk_i32 s0, 0xa0
	s_waitcnt lgkmcnt(0)
	v_mfma_f32_32x32x16_bf16 v[2:17], v[42:45], v[140:143], v[2:17]
	ds_read_b128 v[38:41], v185 offset:32768
	ds_read_b128 v[42:45], v185 offset:40960
	s_waitcnt lgkmcnt(1)
	v_mfma_f32_32x32x16_bf16 v[18:33], v[38:41], v[152:155], v[18:33]
	v_bitop3_b32 v38, v164, v46, s0 bitop3:0x36
	v_add_u32_e32 v186, v47, v38
	s_movk_i32 s0, 0xc0
	s_waitcnt lgkmcnt(0)
	v_mfma_f32_32x32x16_bf16 v[2:17], v[42:45], v[152:155], v[2:17]
	ds_read_b128 v[38:41], v186 offset:32768
	ds_read_b128 v[42:45], v186 offset:40960
	s_waitcnt lgkmcnt(1)
	v_mfma_f32_32x32x16_bf16 v[18:33], v[38:41], v[160:163], v[18:33]
	v_bitop3_b32 v38, v164, v46, s0 bitop3:0x36
	v_add_u32_e32 v189, v47, v38
	s_movk_i32 s0, 0xe0
	s_waitcnt lgkmcnt(0)
	v_mfma_f32_32x32x16_bf16 v[2:17], v[42:45], v[160:163], v[2:17]
	ds_read_b128 v[38:41], v189 offset:32768
	ds_read_b128 v[42:45], v189 offset:40960
	s_waitcnt lgkmcnt(1)
	v_mfma_f32_32x32x16_bf16 v[18:33], v[38:41], v[148:151], v[18:33]
	v_bitop3_b32 v38, v164, v46, s0 bitop3:0x36
	v_add_u32_e32 v190, v47, v38
	s_waitcnt lgkmcnt(0)
	v_mfma_f32_32x32x16_bf16 v[2:17], v[42:45], v[148:151], v[2:17]
	ds_read_b128 v[38:41], v190 offset:32768
	ds_read_b128 v[42:45], v190 offset:40960
	s_waitcnt lgkmcnt(1)
	v_mfma_f32_32x32x16_bf16 v[18:33], v[38:41], v[156:159], v[18:33]
	s_waitcnt lgkmcnt(0)
	v_mfma_f32_32x32x16_bf16 v[2:17], v[42:45], v[156:159], v[2:17]
	s_nop 9
	v_max_f32_e32 v38, v19, v19
	v_max_f32_e32 v39, v18, v18
	v_max_f32_e32 v38, v39, v38
	v_max3_f32 v38, v38, v20, v21
	v_max3_f32 v38, v38, v22, v23
	v_max3_f32 v38, v38, v24, v25
	v_max3_f32 v38, v38, v26, v27
	v_max3_f32 v38, v38, v28, v29
	v_max3_f32 v38, v38, v30, v31
	v_max3_f32 v38, v38, v32, v33
	v_max3_f32 v38, v38, v2, v3
	v_max3_f32 v38, v38, v4, v5
	v_max3_f32 v38, v38, v6, v7
	v_max3_f32 v38, v38, v8, v9
	v_max3_f32 v38, v38, v10, v11
	v_max3_f32 v38, v38, v12, v13
	v_max3_f32 v38, v38, v14, v15
	v_max3_f32 v38, v38, v16, v17
	v_mov_b32_e32 v39, v38
	s_nop 1
	v_permlane32_swap_b32_e32 v38, v39
	v_max_f32_e32 v39, v39, v39
	v_max_f32_e32 v38, v38, v38
	v_max_f32_e32 v38, v38, v39
	v_add_f32_e32 v39, 0x7149f2ca, v38
	v_max_f32_e32 v38, 0xf149f2ca, v38
	v_cmp_ge_f32_e32 vcc, s91, v39
	v_sub_f32_e32 v39, 0xf149f2ca, v38
	v_mul_f32_e32 v39, 0x3e0293ee, v39
	s_cmp_eq_u64 vcc, exec
	v_exp_f32_e32 v39, v39
	s_cselect_b64 vcc, -1, 0
	s_lshl_b32 s30, s28, 7
	v_cndmask_b32_e32 v193, v38, v206, vcc
	s_add_u32 s0, s96, s30
	v_mul_f32_e32 v38, 0xbe0293ee, v193
	s_addc_u32 s1, s97, 0
	v_cndmask_b32_e64 v194, v39, 1.0, vcc
	v_mov_b32_e32 v39, v38
	s_add_u32 s30, s50, s30
	v_fmac_f32_e32 v39, 0x3e0293ee, v33
	s_addc_u32 s31, s51, 0
	v_pk_fma_f32 v[98:99], v[2:3], s[90:91], v[38:39] op_sel_hi:[1,0,0]
	v_lshl_add_u64 v[2:3], s[30:31], 0, v[34:35]
	v_pk_fma_f32 v[102:103], v[6:7], s[90:91], v[38:39] op_sel_hi:[1,0,0]
	v_lshl_add_u64 v[2:3], v[2:3], 0, v[130:131]
	v_lshl_add_u64 v[6:7], s[30:31], 0, v[36:37]
	v_pk_fma_f32 v[106:107], v[10:11], s[90:91], v[38:39] op_sel_hi:[1,0,0]
	v_pk_fma_f32 v[100:101], v[4:5], s[90:91], v[38:39] op_sel_hi:[1,0,0]
	global_load_dwordx4 v[2:5], v[2:3], off
	v_lshl_add_u64 v[6:7], v[6:7], 0, v[130:131]
	v_lshl_add_u64 v[10:11], s[0:1], 0, v[34:35]
	v_pk_fma_f32 v[110:111], v[14:15], s[90:91], v[38:39] op_sel_hi:[1,0,0]
	v_pk_fma_f32 v[104:105], v[8:9], s[90:91], v[38:39] op_sel_hi:[1,0,0]
	global_load_dwordx4 v[6:9], v[6:7], off
	v_lshl_add_u64 v[10:11], v[10:11], 0, v[130:131]
	v_lshl_add_u64 v[14:15], s[0:1], 0, v[36:37]
	v_pk_fma_f32 v[108:109], v[12:13], s[90:91], v[38:39] op_sel_hi:[1,0,0]
	global_load_dwordx4 v[10:13], v[10:11], off
	v_lshl_add_u64 v[14:15], v[14:15], 0, v[130:131]
	v_pk_fma_f32 v[112:113], v[16:17], s[90:91], v[38:39] op_sel_hi:[1,0,0]
	global_load_dwordx4 v[14:17], v[14:15], off
	v_fmamk_f32 v18, v18, 0x3e0293ee, v38
	v_fmamk_f32 v19, v19, 0x3e0293ee, v38
	v_fmamk_f32 v20, v20, 0x3e0293ee, v38
	v_fmamk_f32 v21, v21, 0x3e0293ee, v38
	v_fmamk_f32 v22, v22, 0x3e0293ee, v38
	v_fmamk_f32 v23, v23, 0x3e0293ee, v38
	v_fmamk_f32 v24, v24, 0x3e0293ee, v38
	v_fmamk_f32 v25, v25, 0x3e0293ee, v38
	v_fmamk_f32 v26, v26, 0x3e0293ee, v38
	v_fmamk_f32 v27, v27, 0x3e0293ee, v38
	v_fmamk_f32 v28, v28, 0x3e0293ee, v38
	v_fmamk_f32 v29, v29, 0x3e0293ee, v38
	v_fmamk_f32 v30, v30, 0x3e0293ee, v38
	v_fmamk_f32 v31, v31, 0x3e0293ee, v38
	v_fmamk_f32 v32, v32, 0x3e0293ee, v38
	v_exp_f32_e32 v127, v18
	v_exp_f32_e32 v129, v19
	v_exp_f32_e32 v125, v20
	v_exp_f32_e32 v128, v21
	v_exp_f32_e32 v123, v22
	v_exp_f32_e32 v126, v23
	v_exp_f32_e32 v122, v24
	v_exp_f32_e32 v124, v25
	v_exp_f32_e32 v119, v26
	v_exp_f32_e32 v121, v27
	v_exp_f32_e32 v117, v28
	v_exp_f32_e32 v120, v29
	v_exp_f32_e32 v115, v30
	v_exp_f32_e32 v118, v31
	v_exp_f32_e32 v114, v32
	v_exp_f32_e32 v116, v39
	s_waitcnt vmcnt(0)
	s_waitcnt vmcnt(3)
	ds_write_b128 v187, v[2:5] offset:16384
	s_waitcnt vmcnt(2)
	ds_write_b128 v188, v[6:9] offset:16384
	s_waitcnt vmcnt(1)
	ds_write_b128 v191, v[10:13] offset:49152
	s_waitcnt vmcnt(0)
	ds_write_b128 v192, v[14:17] offset:49152
	s_waitcnt lgkmcnt(0)
	s_barrier
	v_mov_b32_e32 v17, 0
	s_cmp_lt_i32 s68, 3
	v_cmp_gt_u32_e64 s[0:1], 32, v165
	s_cbranch_scc1 .LBB0_584
	s_add_i32 s30, 0, 0x4000
	s_cmp_eq_u32 s20, 0
	v_add_u32_e32 v195, s30, v171
	s_cselect_b64 s[30:31], -1, 0
	s_lshl_b32 s38, s63, 6
	s_add_i32 s38, s69, s38
	v_lshlrev_b32_e32 v2, 2, v168
	s_add_i32 s71, s38, s22
	v_mov_b32_e32 v178, 0
	v_sub_u32_e32 v196, s71, v2
	s_sub_i32 s72, 0, s63
	s_lshl_b32 s73, s28, 8
	s_mul_i32 s74, s28, 0x180
	s_mov_b32 s75, 1
	v_mov_b32_e32 v50, 0
	v_mov_b32_e32 v51, v178
	v_mov_b32_e32 v52, v178
	v_mov_b32_e32 v53, v178
	v_mov_b32_e32 v54, v178
	v_mov_b32_e32 v55, v178
	v_mov_b32_e32 v56, v178
	v_mov_b32_e32 v57, v178
	v_mov_b32_e32 v58, v178
	v_mov_b32_e32 v59, v178
	v_mov_b32_e32 v60, v178
	v_mov_b32_e32 v61, v178
	v_mov_b32_e32 v62, v178
	v_mov_b32_e32 v63, v178
	v_mov_b32_e32 v64, v178
	v_mov_b32_e32 v65, v178
	v_mov_b32_e32 v34, 0
	v_mov_b32_e32 v35, v178
	v_mov_b32_e32 v36, v178
	v_mov_b32_e32 v37, v178
	v_mov_b32_e32 v38, v178
	v_mov_b32_e32 v39, v178
	v_mov_b32_e32 v40, v178
	v_mov_b32_e32 v41, v178
	v_mov_b32_e32 v42, v178
	v_mov_b32_e32 v43, v178
	v_mov_b32_e32 v44, v178
	v_mov_b32_e32 v45, v178
	v_mov_b32_e32 v46, v178
	v_mov_b32_e32 v47, v178
	v_mov_b32_e32 v48, v178
	v_mov_b32_e32 v49, v178
	v_mov_b32_e32 v18, 0
	v_mov_b32_e32 v19, v178
	v_mov_b32_e32 v20, v178
	v_mov_b32_e32 v21, v178
	v_mov_b32_e32 v22, v178
	v_mov_b32_e32 v23, v178
	v_mov_b32_e32 v24, v178
	v_mov_b32_e32 v25, v178
	v_mov_b32_e32 v26, v178
	v_mov_b32_e32 v27, v178
	v_mov_b32_e32 v28, v178
	v_mov_b32_e32 v29, v178
	v_mov_b32_e32 v30, v178
	v_mov_b32_e32 v31, v178
	v_mov_b32_e32 v32, v178
	v_mov_b32_e32 v33, v178
	v_mov_b32_e32 v2, 0
	v_mov_b32_e32 v3, v178
	v_mov_b32_e32 v4, v178
	v_mov_b32_e32 v5, v178
	v_mov_b32_e32 v6, v178
	v_mov_b32_e32 v7, v178
	v_mov_b32_e32 v8, v178
	v_mov_b32_e32 v9, v178
	v_mov_b32_e32 v10, v178
	v_mov_b32_e32 v11, v178
	v_mov_b32_e32 v12, v178
	v_mov_b32_e32 v13, v178
	v_mov_b32_e32 v14, v178
	v_mov_b32_e32 v15, v178
	v_mov_b32_e32 v16, v178
	v_mov_b32_e32 v17, v178
	v_mbcnt_lo_u32_b32 v172, -1, 0
	v_mbcnt_hi_u32_b32 v172, -1, v172
	v_lshrrev_b32_e32 v173, 4, v172
	v_and_b32_e32 v250, 15, v172
	v_xor_b32_e32 v250, v250, v173
	v_lshlrev_b32_e32 v251, 4, v250
	s_lshl_b32 s100, s21, 3
	v_add_u32_e32 v250, s100, v173
	s_and_b32 s100, s21, 1
	s_lshl_b32 s100, s100, 2
	s_lshr_b32 s101, s21, 1
	s_lshl_b32 s101, s101, 4
	s_or_b32 s100, s100, s101
	v_bfe_u32 v173, v172, 2, 2
	v_or_b32_e32 v173, s100, v173
	v_bfe_u32 v174, v172, 4, 1
	v_lshl_or_b32 v173, v174, 3, v173
	v_lshl_or_b32 v250, v173, 8, v250
	v_lshrrev_b32_e32 v173, 5, v172
	v_and_b32_e32 v174, 3, v172
	v_lshlrev_b32_e32 v174, 4, v174
	v_lshl_or_b32 v173, v173, 6, v174
	v_lshl_or_b32 v251, v173, 8, v251
.LBB0_560:
	v_exp_f32_e32 v172, v98
	v_add_f32_e32 v98, 0, v127
	v_add_f32_e32 v98, v129, v98
	v_add_f32_e32 v98, v125, v98
	v_add_f32_e32 v98, v128, v98
	v_add_f32_e32 v98, v123, v98
	v_add_f32_e32 v98, v126, v98
	v_add_f32_e32 v98, v122, v98
	v_add_f32_e32 v98, v124, v98
	v_add_f32_e32 v98, v119, v98
	v_add_f32_e32 v98, v121, v98
	v_add_f32_e32 v98, v117, v98
	v_add_f32_e32 v98, v120, v98
	v_add_f32_e32 v98, v115, v98
	v_exp_f32_e32 v173, v99
	v_add_f32_e32 v98, v118, v98
	v_exp_f32_e32 v174, v100
	v_add_f32_e32 v98, v114, v98
	v_exp_f32_e32 v175, v101
	v_add_f32_e32 v98, v116, v98
	v_exp_f32_e32 v208, v102
	v_add_f32_e32 v98, v172, v98
	v_exp_f32_e32 v209, v103
	v_add_f32_e32 v98, v173, v98
	v_exp_f32_e32 v210, v104
	v_add_f32_e32 v98, v174, v98
	v_exp_f32_e32 v211, v105
	v_add_f32_e32 v98, v175, v98
	v_exp_f32_e32 v212, v106
	v_add_f32_e32 v98, v208, v98
	v_exp_f32_e32 v213, v107
	v_add_f32_e32 v98, v209, v98
	v_exp_f32_e32 v222, v108
	v_add_f32_e32 v98, v210, v98
	v_exp_f32_e32 v223, v109
	v_add_f32_e32 v98, v211, v98
	v_exp_f32_e32 v224, v110
	v_add_f32_e32 v98, v212, v98
	v_exp_f32_e32 v225, v111
	v_add_f32_e32 v98, v213, v98
	v_exp_f32_e32 v226, v112
	v_add_f32_e32 v98, v222, v98
	v_exp_f32_e32 v113, v113
	v_add_f32_e32 v98, v223, v98
	v_add_f32_e32 v98, v224, v98
	v_add_f32_e32 v98, v225, v98
	v_add_f32_e32 v98, v226, v98
	v_add_f32_e32 v198, v113, v98
	v_mov_b32_e32 v199, v198
	v_cvt_pk_bf16_f32 v98, v127, v129
	v_cvt_pk_bf16_f32 v99, v125, v128
	v_cvt_pk_bf16_f32 v100, v123, v126
	v_cvt_pk_bf16_f32 v101, v122, v124
	v_cvt_pk_bf16_f32 v102, v119, v121
	v_cvt_pk_bf16_f32 v103, v117, v120
	v_cvt_pk_bf16_f32 v104, v115, v118
	v_cvt_pk_bf16_f32 v105, v114, v116
	v_cvt_pk_bf16_f32 v106, v172, v173
	v_cvt_pk_bf16_f32 v107, v174, v175
	v_cvt_pk_bf16_f32 v108, v208, v209
	v_cvt_pk_bf16_f32 v109, v210, v211
	v_cvt_pk_bf16_f32 v110, v212, v213
	v_cvt_pk_bf16_f32 v111, v222, v223
	v_cvt_pk_bf16_f32 v112, v224, v225
	v_cvt_pk_bf16_f32 v113, v226, v113
	s_nop 0
	v_permlane32_swap_b32_e32 v198, v199
	v_permlane32_swap_b32_e32 v98, v100
	v_permlane32_swap_b32_e32 v99, v101
	v_permlane32_swap_b32_e32 v102, v104
	v_permlane32_swap_b32_e32 v103, v105
	v_permlane32_swap_b32_e32 v106, v108
	v_permlane32_swap_b32_e32 v107, v109
	v_permlane32_swap_b32_e32 v110, v112
	v_permlane32_swap_b32_e32 v111, v113
	s_add_i32 s38, s75, 1
	s_cmp_lt_u32 s38, s63
	s_cselect_b64 s[40:41], -1, 0
	s_cmp_ge_u32 s38, s63
	s_mov_b64 s[44:45], -1
	s_cbranch_scc0 .LBB0_565
	s_add_i32 s38, s72, s75
	s_add_i32 s38, s38, 1
	s_mul_i32 s42, s38, 0x60000
	s_mul_hi_u32 s43, s38, 0x60000
	s_add_u32 s38, s78, s42
	s_addc_u32 s39, s79, s43
	s_add_u32 s42, s24, s42
	s_addc_u32 s43, s25, s43
	s_mov_b64 s[44:45], 0

.LBB0_567:
	s_lshl_b32 s45, s44, 1
	v_and_b32_e32 v126, 0xff, v250
	v_and_b32_e32 v127, 0xff, v251
	v_lshrrev_b32_e32 v128, 8, v250
	v_lshrrev_b32_e32 v129, 8, v251
	v_mad_u32_u24 v128, v128, s45, v129
	v_add_u32_e32 v129, 0x80, v128
	v_mad_u32_u24 v124, v126, s45, v127
	v_xor_b32_e32 v127, 64, v127
	v_add_u32_e32 v126, 4, v126
	v_mad_u32_u24 v125, v126, s45, v127
	s_lshl_b32 s44, s21, 11
	s_add_i32 m0, s44, 0x8000
	s_mov_b64 s[98:99], s[42:43]
	global_load_lds_dwordx4 v124, s[38:39]
	s_add_i32 m0, s44, 0x8400
	s_nop 0
	global_load_lds_dwordx4 v125, s[38:39]
	ds_read_b128 v[66:69], v180 offset:49152
	ds_read_b128 v[208:211], v182 offset:49152
	ds_read_b128 v[238:241], v180 offset:57344
	ds_read_b128 v[242:245], v182 offset:57344
	ds_read_b128 v[246:249], v183 offset:49152
	s_cmp_lt_u32 s75, s63
	s_cselect_b64 s[38:39], -1, 0
	s_or_b64 s[38:39], s[30:31], s[38:39]
	s_and_b64 vcc, exec, s[38:39]
	v_add_u32_e32 v197, s71, v167
	s_waitcnt lgkmcnt(4)
	v_mfma_f32_32x32x16_bf16 v[82:97], v[66:69], v[136:139], 0
	s_waitcnt lgkmcnt(3)
	v_mfma_f32_32x32x16_bf16 v[82:97], v[208:211], v[144:147], v[82:97]
	ds_read_b128 v[208:211], v183 offset:57344
	s_waitcnt lgkmcnt(3)
	v_mfma_f32_32x32x16_bf16 v[66:81], v[238:241], v[136:139], 0
	ds_read_b128 v[238:241], v184 offset:49152
	s_waitcnt lgkmcnt(3)
	v_mfma_f32_32x32x16_bf16 v[66:81], v[242:245], v[144:147], v[66:81]
	ds_read_b128 v[242:245], v184 offset:57344
	s_waitcnt lgkmcnt(3)
	v_mfma_f32_32x32x16_bf16 v[82:97], v[246:249], v[132:135], v[82:97]
	ds_read_b128 v[246:249], v185 offset:49152
	s_waitcnt lgkmcnt(3)
	v_mfma_f32_32x32x16_bf16 v[66:81], v[208:211], v[132:135], v[66:81]
	ds_read_b128 v[208:211], v185 offset:57344
	s_waitcnt lgkmcnt(3)
	v_mfma_f32_32x32x16_bf16 v[82:97], v[238:241], v[140:143], v[82:97]
	ds_read_b128 v[238:241], v186 offset:49152
	s_waitcnt lgkmcnt(3)
	v_mfma_f32_32x32x16_bf16 v[66:81], v[242:245], v[140:143], v[66:81]
	ds_read_b128 v[242:245], v186 offset:57344
	s_waitcnt lgkmcnt(3)
	v_mfma_f32_32x32x16_bf16 v[82:97], v[246:249], v[152:155], v[82:97]
	ds_read_b128 v[246:249], v189 offset:49152
	s_waitcnt lgkmcnt(3)
	v_mfma_f32_32x32x16_bf16 v[66:81], v[208:211], v[152:155], v[66:81]
	ds_read_b128 v[208:211], v189 offset:57344
	s_waitcnt lgkmcnt(3)
	v_mfma_f32_32x32x16_bf16 v[82:97], v[238:241], v[160:163], v[82:97]
	ds_read_b128 v[238:241], v190 offset:49152
	s_waitcnt lgkmcnt(3)
	v_mfma_f32_32x32x16_bf16 v[66:81], v[242:245], v[160:163], v[66:81]
	ds_read_b128 v[242:245], v190 offset:57344
	s_waitcnt lgkmcnt(3)
	v_mfma_f32_32x32x16_bf16 v[82:97], v[246:249], v[148:151], v[82:97]
	s_waitcnt lgkmcnt(2)
	v_mfma_f32_32x32x16_bf16 v[66:81], v[208:211], v[148:151], v[66:81]
	s_waitcnt lgkmcnt(1)
	v_mfma_f32_32x32x16_bf16 v[82:97], v[238:241], v[156:159], v[82:97]
	s_waitcnt lgkmcnt(0)
	v_mfma_f32_32x32x16_bf16 v[66:81], v[242:245], v[156:159], v[66:81]
	s_cbranch_vccnz .LBB0_563
	v_add_u32_e32 v172, 0xffffff3f, v197
	v_cmp_gt_u32_e32 vcc, s33, v172
	s_cbranch_vccz .LBB0_563
	v_add_u32_e32 v172, v167, v196
	v_add_u32_e32 v173, 0xffffff3f, v172
	v_cmp_lt_u32_e32 vcc, s67, v173
	v_add_u32_e32 v173, 0xffffff1f, v172
	s_nop 0
	v_cndmask_b32_e32 v82, v206, v82, vcc
	v_cmp_lt_u32_e32 vcc, s67, v173
	v_add_u32_e32 v173, 0xffffff3e, v172
	s_nop 0
	v_cndmask_b32_e32 v66, v206, v66, vcc
	v_cmp_lt_u32_e32 vcc, s67, v173
	v_add_u32_e32 v173, 0xffffff1e, v172
	s_nop 0
	v_cndmask_b32_e32 v83, v206, v83, vcc
	v_cmp_lt_u32_e32 vcc, s67, v173
	v_add_u32_e32 v173, 0xffffff3d, v172
	s_nop 0
	v_cndmask_b32_e32 v67, v206, v67, vcc
	v_cmp_lt_u32_e32 vcc, s67, v173
	v_add_u32_e32 v173, 0xffffff1d, v172
	s_nop 0
	v_cndmask_b32_e32 v84, v206, v84, vcc
	v_cmp_lt_u32_e32 vcc, s67, v173
	v_add_u32_e32 v173, 0xffffff3c, v172
	s_nop 0
	v_cndmask_b32_e32 v68, v206, v68, vcc
	v_cmp_lt_u32_e32 vcc, s67, v173
	v_add_u32_e32 v173, 0xffffff1c, v172
	s_nop 0
	v_cndmask_b32_e32 v85, v206, v85, vcc
	v_cmp_lt_u32_e32 vcc, s67, v173
	v_add_u32_e32 v173, 0xffffff37, v172
	s_nop 0
	v_cndmask_b32_e32 v69, v206, v69, vcc
	v_cmp_lt_u32_e32 vcc, s67, v173
	v_add_u32_e32 v173, 0xffffff17, v172
	s_nop 0
	v_cndmask_b32_e32 v86, v206, v86, vcc
	v_cmp_lt_u32_e32 vcc, s67, v173
	v_add_u32_e32 v173, 0xffffff36, v172
	s_nop 0
	v_cndmask_b32_e32 v70, v206, v70, vcc
	v_cmp_lt_u32_e32 vcc, s67, v173
	v_add_u32_e32 v173, 0xffffff16, v172
	s_nop 0
	v_cndmask_b32_e32 v87, v206, v87, vcc
	v_cmp_lt_u32_e32 vcc, s67, v173
	v_add_u32_e32 v173, 0xffffff35, v172
	s_nop 0
	v_cndmask_b32_e32 v71, v206, v71, vcc
	v_cmp_lt_u32_e32 vcc, s67, v173
	v_add_u32_e32 v173, 0xffffff15, v172
	s_nop 0
	v_cndmask_b32_e32 v88, v206, v88, vcc
	v_cmp_lt_u32_e32 vcc, s67, v173
	v_add_u32_e32 v173, 0xffffff34, v172
	s_nop 0
	v_cndmask_b32_e32 v72, v206, v72, vcc
	v_cmp_lt_u32_e32 vcc, s67, v173
	v_add_u32_e32 v173, 0xffffff14, v172
	s_nop 0
	v_cndmask_b32_e32 v89, v206, v89, vcc
	v_cmp_lt_u32_e32 vcc, s67, v173
	v_add_u32_e32 v173, 0xffffff2f, v172
	s_nop 0
	v_cndmask_b32_e32 v73, v206, v73, vcc
	v_cmp_lt_u32_e32 vcc, s67, v173
	v_add_u32_e32 v173, 0xffffff0f, v172
	s_nop 0
	v_cndmask_b32_e32 v90, v206, v90, vcc
	v_cmp_lt_u32_e32 vcc, s67, v173
	v_add_u32_e32 v173, 0xffffff2e, v172
	s_nop 0
	v_cndmask_b32_e32 v74, v206, v74, vcc
	v_cmp_lt_u32_e32 vcc, s67, v173
	v_add_u32_e32 v173, 0xffffff0e, v172
	s_nop 0
	v_cndmask_b32_e32 v91, v206, v91, vcc
	v_cmp_lt_u32_e32 vcc, s67, v173
	v_add_u32_e32 v173, 0xffffff2d, v172
	s_nop 0
	v_cndmask_b32_e32 v75, v206, v75, vcc
	v_cmp_lt_u32_e32 vcc, s67, v173
	v_add_u32_e32 v173, 0xffffff0d, v172
	s_nop 0
	v_cndmask_b32_e32 v92, v206, v92, vcc
	v_cmp_lt_u32_e32 vcc, s67, v173
	v_add_u32_e32 v173, 0xffffff2c, v172
	s_nop 0
	v_cndmask_b32_e32 v76, v206, v76, vcc
	v_cmp_lt_u32_e32 vcc, s67, v173
	v_add_u32_e32 v173, 0xffffff0c, v172
	s_nop 0
	v_cndmask_b32_e32 v93, v206, v93, vcc
	v_cmp_lt_u32_e32 vcc, s67, v173
	v_add_u32_e32 v173, 0xffffff27, v172
	s_nop 0
	v_cndmask_b32_e32 v77, v206, v77, vcc
	v_cmp_lt_u32_e32 vcc, s67, v173
	v_add_u32_e32 v173, 0xffffff07, v172
	s_nop 0
	v_cndmask_b32_e32 v94, v206, v94, vcc
	v_cmp_lt_u32_e32 vcc, s67, v173
	v_add_u32_e32 v173, 0xffffff26, v172
	s_nop 0
	v_cndmask_b32_e32 v78, v206, v78, vcc
	v_cmp_lt_u32_e32 vcc, s67, v173
	v_add_u32_e32 v173, 0xffffff06, v172
	s_nop 0
	v_cndmask_b32_e32 v95, v206, v95, vcc
	v_cmp_lt_u32_e32 vcc, s67, v173
	v_add_u32_e32 v173, 0xffffff25, v172
	s_nop 0
	v_cndmask_b32_e32 v79, v206, v79, vcc
	v_cmp_lt_u32_e32 vcc, s67, v173
	v_add_u32_e32 v173, 0xffffff05, v172
	s_nop 0
	v_cndmask_b32_e32 v96, v206, v96, vcc
	v_cmp_lt_u32_e32 vcc, s67, v173
	v_add_u32_e32 v173, 0xffffff24, v172
	v_add_u32_e32 v172, 0xffffff04, v172
	v_cndmask_b32_e32 v80, v206, v80, vcc
	v_cmp_lt_u32_e32 vcc, s67, v173
	s_nop 1
	v_cndmask_b32_e32 v97, v206, v97, vcc
	v_cmp_lt_u32_e32 vcc, s67, v172
	s_nop 1
	v_cndmask_b32_e32 v81, v206, v81, vcc
.LBB0_563:
	ds_read_b64_tr_b16 v[208:209], v176 offset:0
	ds_read_b64_tr_b16 v[210:211], v176 offset:0x800
	ds_read_b64_tr_b16 v[222:223], v176 offset:0x1000
	ds_read_b64_tr_b16 v[224:225], v176 offset:0x1800
	ds_read_b64_tr_b16 v[226:227], v176 offset:0x2000
	ds_read_b64_tr_b16 v[228:229], v176 offset:0x2800
	ds_read_b64_tr_b16 v[230:231], v176 offset:0x3000
	ds_read_b64_tr_b16 v[232:233], v176 offset:0x3800
	s_waitcnt lgkmcnt(0)
	s_nop 0
	v_mfma_f32_32x32x16_bf16 v[50:65], v[98:101], v[208:211], v[50:65]
	ds_read_b64_tr_b16 v[208:209], v176 offset:0x200
	ds_read_b64_tr_b16 v[210:211], v176 offset:0xa00
	v_mfma_f32_32x32x16_bf16 v[50:65], v[102:105], v[222:225], v[50:65]
	ds_read_b64_tr_b16 v[222:223], v176 offset:0x1200
	ds_read_b64_tr_b16 v[224:225], v176 offset:0x1a00
	v_mfma_f32_32x32x16_bf16 v[50:65], v[106:109], v[226:229], v[50:65]
	ds_read_b64_tr_b16 v[226:227], v176 offset:0x2200
	ds_read_b64_tr_b16 v[228:229], v176 offset:0x2a00
	v_mfma_f32_32x32x16_bf16 v[50:65], v[110:113], v[230:233], v[50:65]
	ds_read_b64_tr_b16 v[230:231], v176 offset:0x3200
	ds_read_b64_tr_b16 v[232:233], v176 offset:0x3a00
	s_waitcnt lgkmcnt(0)
	v_mfma_f32_32x32x16_bf16 v[34:49], v[98:101], v[208:211], v[34:49]
	ds_read_b64_tr_b16 v[208:209], v176 offset:0x400
	ds_read_b64_tr_b16 v[210:211], v176 offset:0xc00
	v_mfma_f32_32x32x16_bf16 v[34:49], v[102:105], v[222:225], v[34:49]
	ds_read_b64_tr_b16 v[222:223], v176 offset:0x1400
	ds_read_b64_tr_b16 v[224:225], v176 offset:0x1c00
	v_mfma_f32_32x32x16_bf16 v[34:49], v[106:109], v[226:229], v[34:49]
	ds_read_b64_tr_b16 v[226:227], v176 offset:0x2400
	ds_read_b64_tr_b16 v[228:229], v176 offset:0x2c00
	v_mfma_f32_32x32x16_bf16 v[34:49], v[110:113], v[230:233], v[34:49]
	ds_read_b64_tr_b16 v[230:231], v176 offset:0x3400
	ds_read_b64_tr_b16 v[232:233], v176 offset:0x3c00
	s_waitcnt lgkmcnt(0)
	v_mfma_f32_32x32x16_bf16 v[18:33], v[98:101], v[208:211], v[18:33]
	ds_read_b64_tr_b16 v[208:209], v176 offset:0x600
	ds_read_b64_tr_b16 v[210:211], v176 offset:0xe00
	v_mfma_f32_32x32x16_bf16 v[18:33], v[102:105], v[222:225], v[18:33]
	ds_read_b64_tr_b16 v[222:223], v176 offset:0x1600
	ds_read_b64_tr_b16 v[224:225], v176 offset:0x1e00
	v_mfma_f32_32x32x16_bf16 v[18:33], v[106:109], v[226:229], v[18:33]
	ds_read_b64_tr_b16 v[226:227], v176 offset:0x2600
	ds_read_b64_tr_b16 v[228:229], v176 offset:0x2e00
	v_mfma_f32_32x32x16_bf16 v[18:33], v[110:113], v[230:233], v[18:33]
	ds_read_b64_tr_b16 v[230:231], v176 offset:0x3600
	ds_read_b64_tr_b16 v[232:233], v176 offset:0x3e00
	s_waitcnt lgkmcnt(0)
	v_mfma_f32_32x32x16_bf16 v[2:17], v[98:101], v[208:211], v[2:17]
	v_max_f32_e32 v98, v83, v83
	v_max_f32_e32 v99, v82, v82
	v_max_f32_e32 v98, v99, v98
	v_max3_f32 v98, v98, v84, v85
	v_max3_f32 v98, v98, v86, v87
	v_max3_f32 v98, v98, v88, v89
	v_max3_f32 v98, v98, v90, v91
	v_max3_f32 v98, v98, v92, v93
	v_max3_f32 v98, v98, v94, v95
	v_mfma_f32_32x32x16_bf16 v[2:17], v[102:105], v[222:225], v[2:17]
	v_max3_f32 v98, v98, v96, v97
	v_max3_f32 v98, v98, v66, v67
	v_max3_f32 v98, v98, v68, v69
	v_max3_f32 v98, v98, v70, v71
	v_max3_f32 v98, v98, v72, v73
	v_max3_f32 v98, v98, v74, v75
	v_max3_f32 v98, v98, v76, v77
	v_max3_f32 v98, v98, v78, v79
	v_mfma_f32_32x32x16_bf16 v[2:17], v[106:109], v[226:229], v[2:17]
	v_max3_f32 v98, v98, v80, v81
	v_mov_b32_e32 v99, v98
	s_nop 1
	v_permlane32_swap_b32_e32 v98, v99
	v_max_f32_e32 v99, v99, v99
	v_max_f32_e32 v98, v98, v98
	v_max_f32_e32 v98, v98, v99
	v_sub_f32_e32 v99, v98, v193
	v_cmp_ge_f32_e32 vcc, s91, v99
	v_max_f32_e32 v99, v193, v193
	v_max_f32_e32 v209, v99, v98
	v_mfma_f32_32x32x16_bf16 v[2:17], v[110:113], v[230:233], v[2:17]
	v_sub_f32_e32 v98, v193, v209
	v_mul_f32_e32 v98, 0x3e0293ee, v98
	v_exp_f32_e32 v98, v98
	s_cmp_eq_u64 vcc, exec
	s_waitcnt lgkmcnt(0)
	s_waitcnt vmcnt(0)
	s_barrier
	s_cselect_b64 s[38:39], -1, 0
	s_waitcnt vmcnt(0)
	v_cndmask_b32_e64 v208, v98, 1.0, s[38:39]
	v_cmp_gt_f32_e32 vcc, 1.0, v208
	s_lshl_b32 s42, s21, 11
	s_mov_b32 m0, s42
	s_nop 0
	global_load_lds_dwordx4 v128, s[98:99]
	s_add_i32 m0, s42, 0x400
	s_nop 0
	global_load_lds_dwordx4 v129, s[98:99]
	s_cbranch_vccz .LBB0_571
	s_and_saveexec_b64 s[42:43], s[0:1]
	ds_write_b32 v177, v208 offset:128
	s_or_b64 exec, exec, s[42:43]
	s_waitcnt lgkmcnt(0)
	v_add_u32_e32 v110, s70, v164
	ds_read_b128 v[98:101], v110 offset:224
	ds_read_b128 v[102:105], v110 offset:192
	ds_read_b128 v[106:109], v110 offset:160
	ds_read_b128 v[110:113], v110 offset:128
	s_waitcnt lgkmcnt(3)
	v_pk_mul_f32 v[62:63], v[62:63], v[98:99]
	s_waitcnt lgkmcnt(2)
	v_pk_mul_f32 v[58:59], v[58:59], v[102:103]
	s_waitcnt lgkmcnt(1)
	v_pk_mul_f32 v[54:55], v[54:55], v[106:107]
	v_pk_mul_f32 v[64:65], v[64:65], v[100:101]
	v_pk_mul_f32 v[60:61], v[60:61], v[104:105]
	v_pk_mul_f32 v[56:57], v[56:57], v[108:109]
	s_waitcnt lgkmcnt(0)
	v_pk_mul_f32 v[52:53], v[52:53], v[112:113]
	v_pk_mul_f32 v[50:51], v[50:51], v[110:111]
	v_pk_mul_f32 v[46:47], v[46:47], v[98:99]
	v_pk_mul_f32 v[42:43], v[42:43], v[102:103]
	v_pk_mul_f32 v[38:39], v[38:39], v[106:107]
	v_pk_mul_f32 v[48:49], v[48:49], v[100:101]
	v_pk_mul_f32 v[44:45], v[44:45], v[104:105]
	v_pk_mul_f32 v[40:41], v[40:41], v[108:109]
	v_pk_mul_f32 v[36:37], v[36:37], v[112:113]
	v_pk_mul_f32 v[34:35], v[34:35], v[110:111]
	v_pk_mul_f32 v[30:31], v[30:31], v[98:99]
	v_pk_mul_f32 v[26:27], v[26:27], v[102:103]
	v_pk_mul_f32 v[22:23], v[22:23], v[106:107]
	v_pk_mul_f32 v[32:33], v[32:33], v[100:101]
	v_pk_mul_f32 v[28:29], v[28:29], v[104:105]
	v_pk_mul_f32 v[24:25], v[24:25], v[108:109]
	v_pk_mul_f32 v[20:21], v[20:21], v[112:113]
	v_pk_mul_f32 v[18:19], v[18:19], v[110:111]
	v_pk_mul_f32 v[14:15], v[14:15], v[98:99]
	v_pk_mul_f32 v[10:11], v[10:11], v[102:103]
	v_pk_mul_f32 v[6:7], v[6:7], v[106:107]
	v_pk_mul_f32 v[16:17], v[16:17], v[100:101]
	v_pk_mul_f32 v[12:13], v[12:13], v[104:105]
	v_pk_mul_f32 v[8:9], v[8:9], v[108:109]
	v_pk_mul_f32 v[4:5], v[4:5], v[112:113]
	v_pk_mul_f32 v[2:3], v[2:3], v[110:111]
.LBB0_571:
	s_waitcnt lgkmcnt(0)
	v_cndmask_b32_e64 v193, v209, v193, s[38:39]
	v_mul_f32_e32 v172, 0xbe0293ee, v193
	v_fmamk_f32 v82, v82, 0x3e0293ee, v172
	v_fmamk_f32 v83, v83, 0x3e0293ee, v172
	v_fmamk_f32 v84, v84, 0x3e0293ee, v172
	v_fmamk_f32 v85, v85, 0x3e0293ee, v172
	v_fmamk_f32 v86, v86, 0x3e0293ee, v172
	v_fmamk_f32 v87, v87, 0x3e0293ee, v172
	v_fmamk_f32 v88, v88, 0x3e0293ee, v172
	v_fmamk_f32 v89, v89, 0x3e0293ee, v172
	v_fmamk_f32 v90, v90, 0x3e0293ee, v172
	v_fmamk_f32 v91, v91, 0x3e0293ee, v172
	v_fmamk_f32 v92, v92, 0x3e0293ee, v172
	v_fmamk_f32 v93, v93, 0x3e0293ee, v172
	v_fmamk_f32 v94, v94, 0x3e0293ee, v172
	v_fmamk_f32 v95, v95, 0x3e0293ee, v172
	v_fmamk_f32 v96, v96, 0x3e0293ee, v172
	v_fmamk_f32 v97, v97, 0x3e0293ee, v172
	v_fmamk_f32 v66, v66, 0x3e0293ee, v172
	v_fmamk_f32 v67, v67, 0x3e0293ee, v172
	v_fmamk_f32 v68, v68, 0x3e0293ee, v172
	v_fmamk_f32 v69, v69, 0x3e0293ee, v172
	v_fmamk_f32 v70, v70, 0x3e0293ee, v172
	v_fmamk_f32 v71, v71, 0x3e0293ee, v172
	v_fmamk_f32 v72, v72, 0x3e0293ee, v172
	v_fmamk_f32 v73, v73, 0x3e0293ee, v172
	v_fmamk_f32 v74, v74, 0x3e0293ee, v172
	v_fmamk_f32 v75, v75, 0x3e0293ee, v172
	v_fmamk_f32 v76, v76, 0x3e0293ee, v172
	v_fmamk_f32 v77, v77, 0x3e0293ee, v172
	v_fmamk_f32 v78, v78, 0x3e0293ee, v172
	v_fmamk_f32 v79, v79, 0x3e0293ee, v172
	v_fmamk_f32 v80, v80, 0x3e0293ee, v172
	v_fmac_f32_e32 v172, 0x3e0293ee, v81
	v_exp_f32_e32 v81, v82
	v_exp_f32_e32 v82, v83
	v_exp_f32_e32 v83, v84
	v_exp_f32_e32 v84, v85
	v_exp_f32_e32 v85, v86
	v_exp_f32_e32 v86, v87
	v_exp_f32_e32 v87, v88
	v_exp_f32_e32 v88, v89
	v_exp_f32_e32 v89, v90
	v_exp_f32_e32 v90, v91
	v_exp_f32_e32 v91, v92
	v_exp_f32_e32 v92, v93
	v_exp_f32_e32 v93, v94
	v_exp_f32_e32 v94, v95
	v_exp_f32_e32 v95, v96
	v_exp_f32_e32 v96, v97
	v_exp_f32_e32 v97, v66
	v_add_f32_e32 v66, 0, v81
	v_add_f32_e32 v66, v82, v66
	v_add_f32_e32 v66, v83, v66
	v_add_f32_e32 v66, v84, v66
	v_add_f32_e32 v66, v85, v66
	v_add_f32_e32 v66, v86, v66
	v_add_f32_e32 v66, v87, v66
	v_add_f32_e32 v66, v88, v66
	v_add_f32_e32 v66, v89, v66
	v_add_f32_e32 v66, v90, v66
	v_add_f32_e32 v66, v91, v66
	v_add_f32_e32 v66, v92, v66
	v_add_f32_e32 v66, v93, v66
	v_exp_f32_e32 v173, v67
	v_add_f32_e32 v66, v94, v66
	v_exp_f32_e32 v174, v68
	v_add_f32_e32 v66, v95, v66
	v_exp_f32_e32 v175, v69
	v_add_f32_e32 v66, v96, v66
	v_exp_f32_e32 v114, v70
	v_add_f32_e32 v66, v97, v66
	v_exp_f32_e32 v211, v71
	v_add_f32_e32 v66, v173, v66
	v_exp_f32_e32 v212, v72
	v_add_f32_e32 v66, v174, v66
	v_exp_f32_e32 v213, v73
	v_add_f32_e32 v66, v175, v66
	v_exp_f32_e32 v74, v74
	v_add_f32_e32 v66, v114, v66
	v_exp_f32_e32 v75, v75
	v_add_f32_e32 v66, v211, v66
	v_exp_f32_e32 v76, v76
	v_add_f32_e32 v66, v212, v66
	v_exp_f32_e32 v77, v77
	v_add_f32_e32 v66, v213, v66
	v_exp_f32_e32 v78, v78
	v_add_f32_e32 v66, v74, v66
	v_exp_f32_e32 v79, v79
	v_add_f32_e32 v66, v75, v66
	v_exp_f32_e32 v80, v80
	v_add_f32_e32 v66, v76, v66
	v_exp_f32_e32 v172, v172
	v_add_f32_e32 v66, v77, v66
	v_add_f32_e32 v66, v78, v66
	v_add_f32_e32 v66, v79, v66
	v_add_f32_e32 v66, v80, v66
	v_add_f32_e32 v209, v172, v66
	v_mov_b32_e32 v210, v209
	v_cvt_pk_bf16_f32 v66, v81, v82
	v_cvt_pk_bf16_f32 v67, v83, v84
	v_cvt_pk_bf16_f32 v68, v85, v86
	v_cvt_pk_bf16_f32 v69, v87, v88
	v_cvt_pk_bf16_f32 v70, v89, v90
	v_cvt_pk_bf16_f32 v71, v91, v92
	v_cvt_pk_bf16_f32 v72, v93, v94
	v_cvt_pk_bf16_f32 v73, v95, v96
	v_cvt_pk_bf16_f32 v90, v97, v173
	v_cvt_pk_bf16_f32 v91, v174, v175
	v_cvt_pk_bf16_f32 v92, v114, v211
	v_cvt_pk_bf16_f32 v93, v212, v213
	v_cvt_pk_bf16_f32 v94, v74, v75
	v_cvt_pk_bf16_f32 v95, v76, v77
	v_cvt_pk_bf16_f32 v96, v78, v79
	v_cvt_pk_bf16_f32 v97, v80, v172
	s_nop 1
	v_permlane32_swap_b32_e32 v209, v210
	v_permlane32_swap_b32_e32 v66, v68
	v_permlane32_swap_b32_e32 v67, v69
	v_permlane32_swap_b32_e32 v70, v72
	v_permlane32_swap_b32_e32 v71, v73
	v_permlane32_swap_b32_e32 v90, v92
	v_permlane32_swap_b32_e32 v91, v93
	v_permlane32_swap_b32_e32 v94, v96
	v_permlane32_swap_b32_e32 v95, v97
	s_add_i32 s44, s75, 2
	s_cmp_ge_u32 s44, s63
	s_mov_b64 s[42:43], -1
	s_cbranch_scc0 .LBB0_576
	s_add_i32 s38, s72, s75
	s_add_i32 s38, s38, 2
	s_mul_i32 s100, s38, 0x60000
	s_mul_hi_u32 s101, s38, 0x60000
	s_add_u32 s38, s78, s100
	s_addc_u32 s39, s79, s101
	s_add_u32 s100, s24, s100
	s_addc_u32 s101, s25, s101
	s_mov_b64 s[42:43], 0
.LBB0_576:
	s_andn2_b64 vcc, exec, s[42:43]
	s_mov_b64 s[42:43], 0xc00
	s_cbranch_vccnz .LBB0_578
	s_add_u32 s38, s96, s74
	s_addc_u32 s39, s97, 0
	s_add_u32 s100, s50, s74
	s_addc_u32 s101, s51, 0
	s_mov_b64 s[42:43], s[28:29]
.LBB0_578:
	s_lshl_b32 s43, s42, 1
	v_and_b32_e32 v86, 0xff, v250
	v_and_b32_e32 v87, 0xff, v251
	v_lshrrev_b32_e32 v88, 8, v250
	v_lshrrev_b32_e32 v89, 8, v251
	v_mad_u32_u24 v88, v88, s43, v89
	v_add_u32_e32 v89, 0x80, v88
	v_mad_u32_u24 v84, v86, s43, v87
	v_xor_b32_e32 v87, 64, v87
	v_add_u32_e32 v86, 4, v86
	v_mad_u32_u24 v85, v86, s43, v87
	s_lshl_b32 s42, s21, 11
	s_add_i32 m0, s42, 0xc000
	s_nop 0
	global_load_lds_dwordx4 v84, s[38:39]
	s_add_i32 m0, s42, 0xc400
	s_nop 0
	global_load_lds_dwordx4 v85, s[38:39]
	ds_read_b128 v[98:101], v180 offset:32768
	ds_read_b128 v[172:175], v182 offset:32768
	ds_read_b128 v[238:241], v180 offset:40960
	ds_read_b128 v[242:245], v182 offset:40960
	ds_read_b128 v[246:249], v183 offset:32768
	s_or_b64 s[40:41], s[30:31], s[40:41]
	s_and_b64 vcc, exec, s[40:41]
	s_waitcnt lgkmcnt(4)
	v_mfma_f32_32x32x16_bf16 v[114:129], v[98:101], v[136:139], 0
	s_waitcnt lgkmcnt(3)
	v_mfma_f32_32x32x16_bf16 v[114:129], v[172:175], v[144:147], v[114:129]
	ds_read_b128 v[172:175], v183 offset:40960
	s_waitcnt lgkmcnt(3)
	v_mfma_f32_32x32x16_bf16 v[98:113], v[238:241], v[136:139], 0
	ds_read_b128 v[238:241], v184 offset:32768
	s_waitcnt lgkmcnt(3)
	v_mfma_f32_32x32x16_bf16 v[98:113], v[242:245], v[144:147], v[98:113]
	ds_read_b128 v[242:245], v184 offset:40960
	s_waitcnt lgkmcnt(3)
	v_mfma_f32_32x32x16_bf16 v[114:129], v[246:249], v[132:135], v[114:129]
	ds_read_b128 v[246:249], v185 offset:32768
	s_waitcnt lgkmcnt(3)
	v_mfma_f32_32x32x16_bf16 v[98:113], v[172:175], v[132:135], v[98:113]
	ds_read_b128 v[172:175], v185 offset:40960
	s_waitcnt lgkmcnt(3)
	v_mfma_f32_32x32x16_bf16 v[114:129], v[238:241], v[140:143], v[114:129]
	ds_read_b128 v[238:241], v186 offset:32768
	s_waitcnt lgkmcnt(3)
	v_mfma_f32_32x32x16_bf16 v[98:113], v[242:245], v[140:143], v[98:113]
	ds_read_b128 v[242:245], v186 offset:40960
	s_waitcnt lgkmcnt(3)
	v_mfma_f32_32x32x16_bf16 v[114:129], v[246:249], v[152:155], v[114:129]
	ds_read_b128 v[246:249], v189 offset:32768
	s_waitcnt lgkmcnt(3)
	v_mfma_f32_32x32x16_bf16 v[98:113], v[172:175], v[152:155], v[98:113]
	ds_read_b128 v[172:175], v189 offset:40960
	s_waitcnt lgkmcnt(3)
	v_mfma_f32_32x32x16_bf16 v[114:129], v[238:241], v[160:163], v[114:129]
	ds_read_b128 v[238:241], v190 offset:32768
	s_waitcnt lgkmcnt(3)
	v_mfma_f32_32x32x16_bf16 v[98:113], v[242:245], v[160:163], v[98:113]
	ds_read_b128 v[242:245], v190 offset:40960
	s_waitcnt lgkmcnt(3)
	v_mfma_f32_32x32x16_bf16 v[114:129], v[246:249], v[148:151], v[114:129]
	s_waitcnt lgkmcnt(2)
	v_mfma_f32_32x32x16_bf16 v[98:113], v[172:175], v[148:151], v[98:113]
	s_waitcnt lgkmcnt(1)
	v_mfma_f32_32x32x16_bf16 v[114:129], v[238:241], v[156:159], v[114:129]
	s_waitcnt lgkmcnt(0)
	v_mfma_f32_32x32x16_bf16 v[98:113], v[242:245], v[156:159], v[98:113]
	s_cbranch_vccnz .LBB0_574
	v_add_u32_e32 v172, 0xfffffeff, v197
	v_cmp_gt_u32_e32 vcc, s33, v172
	s_cbranch_vccz .LBB0_574
	v_add_u32_e32 v172, v167, v196
	v_add_co_u32_e32 v173, vcc, 0xfffffeff, v172
	v_add_u32_e32 v173, 0xfffffedf, v172
	s_nop 1
	v_cndmask_b32_e32 v114, v114, v206, vcc
	v_cmp_lt_u32_e32 vcc, s67, v173
	v_add_u32_e32 v173, 0xfffffefe, v172
	s_nop 0
	v_cndmask_b32_e32 v98, v206, v98, vcc
	v_cmp_lt_u32_e32 vcc, s67, v173
	v_add_u32_e32 v173, 0xfffffede, v172
	s_nop 0
	v_cndmask_b32_e32 v115, v206, v115, vcc
	v_cmp_lt_u32_e32 vcc, s67, v173
	v_add_u32_e32 v173, 0xfffffefd, v172
	s_nop 0
	v_cndmask_b32_e32 v99, v206, v99, vcc
	v_cmp_lt_u32_e32 vcc, s67, v173
	v_add_u32_e32 v173, 0xfffffedd, v172
	s_nop 0
	v_cndmask_b32_e32 v116, v206, v116, vcc
	v_cmp_lt_u32_e32 vcc, s67, v173
	v_add_u32_e32 v173, 0xfffffefc, v172
	s_nop 0
	v_cndmask_b32_e32 v100, v206, v100, vcc
	v_cmp_lt_u32_e32 vcc, s67, v173
	v_add_u32_e32 v173, 0xfffffedc, v172
	s_nop 0
	v_cndmask_b32_e32 v117, v206, v117, vcc
	v_cmp_lt_u32_e32 vcc, s67, v173
	v_add_u32_e32 v173, 0xfffffef7, v172
	s_nop 0
	v_cndmask_b32_e32 v101, v206, v101, vcc
	v_cmp_lt_u32_e32 vcc, s67, v173
	v_add_u32_e32 v173, 0xfffffed7, v172
	s_nop 0
	v_cndmask_b32_e32 v118, v206, v118, vcc
	v_cmp_lt_u32_e32 vcc, s67, v173
	v_add_u32_e32 v173, 0xfffffef6, v172
	s_nop 0
	v_cndmask_b32_e32 v102, v206, v102, vcc
	v_cmp_lt_u32_e32 vcc, s67, v173
	v_add_u32_e32 v173, 0xfffffed6, v172
	s_nop 0
	v_cndmask_b32_e32 v119, v206, v119, vcc
	v_cmp_lt_u32_e32 vcc, s67, v173
	v_add_u32_e32 v173, 0xfffffef5, v172
	s_nop 0
	v_cndmask_b32_e32 v103, v206, v103, vcc
	v_cmp_lt_u32_e32 vcc, s67, v173
	v_add_u32_e32 v173, 0xfffffed5, v172
	s_nop 0
	v_cndmask_b32_e32 v120, v206, v120, vcc
	v_cmp_lt_u32_e32 vcc, s67, v173
	v_add_u32_e32 v173, 0xfffffef4, v172
	s_nop 0
	v_cndmask_b32_e32 v104, v206, v104, vcc
	v_cmp_lt_u32_e32 vcc, s67, v173
	v_add_u32_e32 v173, 0xfffffed4, v172
	s_nop 0
	v_cndmask_b32_e32 v121, v206, v121, vcc
	v_cmp_lt_u32_e32 vcc, s67, v173
	v_add_u32_e32 v173, 0xfffffeef, v172
	s_nop 0
	v_cndmask_b32_e32 v105, v206, v105, vcc
	v_cmp_lt_u32_e32 vcc, s67, v173
	v_add_u32_e32 v173, 0xfffffecf, v172
	s_nop 0
	v_cndmask_b32_e32 v122, v206, v122, vcc
	v_cmp_lt_u32_e32 vcc, s67, v173
	v_add_u32_e32 v173, 0xfffffeee, v172
	s_nop 0
	v_cndmask_b32_e32 v106, v206, v106, vcc
	v_cmp_lt_u32_e32 vcc, s67, v173
	v_add_u32_e32 v173, 0xfffffece, v172
	s_nop 0
	v_cndmask_b32_e32 v123, v206, v123, vcc
	v_cmp_lt_u32_e32 vcc, s67, v173
	v_add_u32_e32 v173, 0xfffffeed, v172
	s_nop 0
	v_cndmask_b32_e32 v107, v206, v107, vcc
	v_cmp_lt_u32_e32 vcc, s67, v173
	v_add_u32_e32 v173, 0xfffffecd, v172
	s_nop 0
	v_cndmask_b32_e32 v124, v206, v124, vcc
	v_cmp_lt_u32_e32 vcc, s67, v173
	v_add_u32_e32 v173, 0xfffffeec, v172
	s_nop 0
	v_cndmask_b32_e32 v108, v206, v108, vcc
	v_cmp_lt_u32_e32 vcc, s67, v173
	v_add_u32_e32 v173, 0xfffffecc, v172
	s_nop 0
	v_cndmask_b32_e32 v125, v206, v125, vcc
	v_cmp_lt_u32_e32 vcc, s67, v173
	v_add_u32_e32 v173, 0xfffffee7, v172
	s_nop 0
	v_cndmask_b32_e32 v109, v206, v109, vcc
	v_cmp_lt_u32_e32 vcc, s67, v173
	v_add_u32_e32 v173, 0xfffffec7, v172
	s_nop 0
	v_cndmask_b32_e32 v126, v206, v126, vcc
	v_cmp_lt_u32_e32 vcc, s67, v173
	v_add_u32_e32 v173, 0xfffffee6, v172
	s_nop 0
	v_cndmask_b32_e32 v110, v206, v110, vcc
	v_cmp_lt_u32_e32 vcc, s67, v173
	v_add_u32_e32 v173, 0xfffffec6, v172
	s_nop 0
	v_cndmask_b32_e32 v127, v206, v127, vcc
	v_cmp_lt_u32_e32 vcc, s67, v173
	v_add_u32_e32 v173, 0xfffffee5, v172
	s_nop 0
	v_cndmask_b32_e32 v111, v206, v111, vcc
	v_cmp_lt_u32_e32 vcc, s67, v173
	v_add_u32_e32 v173, 0xfffffec5, v172
	s_nop 0
	v_cndmask_b32_e32 v128, v206, v128, vcc
	v_cmp_lt_u32_e32 vcc, s67, v173
	v_add_u32_e32 v173, 0xfffffee4, v172
	v_add_u32_e32 v172, 0xfffffec4, v172
	v_cndmask_b32_e32 v112, v206, v112, vcc
	v_cmp_lt_u32_e32 vcc, s67, v173
	s_nop 1
	v_cndmask_b32_e32 v129, v206, v129, vcc
	v_cmp_lt_u32_e32 vcc, s67, v172
	s_nop 1
	v_cndmask_b32_e32 v113, v206, v113, vcc
.LBB0_574:
	ds_read_b64_tr_b16 v[222:223], v195 offset:0
	ds_read_b64_tr_b16 v[224:225], v195 offset:0x800
	ds_read_b64_tr_b16 v[226:227], v195 offset:0x1000
	ds_read_b64_tr_b16 v[228:229], v195 offset:0x1800
	ds_read_b64_tr_b16 v[230:231], v195 offset:0x2000
	ds_read_b64_tr_b16 v[232:233], v195 offset:0x2800
	ds_read_b64_tr_b16 v[234:235], v195 offset:0x3000
	ds_read_b64_tr_b16 v[236:237], v195 offset:0x3800
	s_waitcnt lgkmcnt(0)
	s_nop 0
	v_mfma_f32_32x32x16_bf16 v[50:65], v[66:69], v[222:225], v[50:65]
	ds_read_b64_tr_b16 v[222:223], v195 offset:0x200
	ds_read_b64_tr_b16 v[224:225], v195 offset:0xa00
	v_mfma_f32_32x32x16_bf16 v[50:65], v[70:73], v[226:229], v[50:65]
	ds_read_b64_tr_b16 v[226:227], v195 offset:0x1200
	ds_read_b64_tr_b16 v[228:229], v195 offset:0x1a00
	v_mfma_f32_32x32x16_bf16 v[50:65], v[90:93], v[230:233], v[50:65]
	ds_read_b64_tr_b16 v[230:231], v195 offset:0x2200
	ds_read_b64_tr_b16 v[232:233], v195 offset:0x2a00
	v_mfma_f32_32x32x16_bf16 v[50:65], v[94:97], v[234:237], v[50:65]
	ds_read_b64_tr_b16 v[234:235], v195 offset:0x3200
	ds_read_b64_tr_b16 v[236:237], v195 offset:0x3a00
	s_waitcnt lgkmcnt(0)
	v_mfma_f32_32x32x16_bf16 v[34:49], v[66:69], v[222:225], v[34:49]
	ds_read_b64_tr_b16 v[222:223], v195 offset:0x400
	ds_read_b64_tr_b16 v[224:225], v195 offset:0xc00
	v_mfma_f32_32x32x16_bf16 v[34:49], v[70:73], v[226:229], v[34:49]
	ds_read_b64_tr_b16 v[226:227], v195 offset:0x1400
	ds_read_b64_tr_b16 v[228:229], v195 offset:0x1c00
	v_mfma_f32_32x32x16_bf16 v[34:49], v[90:93], v[230:233], v[34:49]
	ds_read_b64_tr_b16 v[230:231], v195 offset:0x2400
	ds_read_b64_tr_b16 v[232:233], v195 offset:0x2c00
	v_mfma_f32_32x32x16_bf16 v[34:49], v[94:97], v[234:237], v[34:49]
	ds_read_b64_tr_b16 v[234:235], v195 offset:0x3400
	ds_read_b64_tr_b16 v[236:237], v195 offset:0x3c00
	s_waitcnt lgkmcnt(0)
	v_mfma_f32_32x32x16_bf16 v[18:33], v[66:69], v[222:225], v[18:33]
	ds_read_b64_tr_b16 v[222:223], v195 offset:0x600
	ds_read_b64_tr_b16 v[224:225], v195 offset:0xe00
	v_mfma_f32_32x32x16_bf16 v[18:33], v[70:73], v[226:229], v[18:33]
	ds_read_b64_tr_b16 v[226:227], v195 offset:0x1600
	ds_read_b64_tr_b16 v[228:229], v195 offset:0x1e00
	v_mfma_f32_32x32x16_bf16 v[18:33], v[90:93], v[230:233], v[18:33]
	ds_read_b64_tr_b16 v[230:231], v195 offset:0x2600
	ds_read_b64_tr_b16 v[232:233], v195 offset:0x2e00
	v_mfma_f32_32x32x16_bf16 v[18:33], v[94:97], v[234:237], v[18:33]
	ds_read_b64_tr_b16 v[234:235], v195 offset:0x3600
	ds_read_b64_tr_b16 v[236:237], v195 offset:0x3e00
	s_waitcnt lgkmcnt(0)
	v_mfma_f32_32x32x16_bf16 v[2:17], v[66:69], v[222:225], v[2:17]
	v_max_f32_e32 v66, v115, v115
	v_max_f32_e32 v67, v114, v114
	v_max_f32_e32 v66, v67, v66
	v_max3_f32 v66, v66, v116, v117
	v_max3_f32 v66, v66, v118, v119
	v_max3_f32 v66, v66, v120, v121
	v_max3_f32 v66, v66, v122, v123
	v_max3_f32 v66, v66, v124, v125
	v_max3_f32 v66, v66, v126, v127
	v_mfma_f32_32x32x16_bf16 v[2:17], v[70:73], v[226:229], v[2:17]
	v_max3_f32 v66, v66, v128, v129
	v_max3_f32 v66, v66, v98, v99
	v_max3_f32 v66, v66, v100, v101
	v_max3_f32 v66, v66, v102, v103
	v_max3_f32 v66, v66, v104, v105
	v_max3_f32 v66, v66, v106, v107
	v_max3_f32 v66, v66, v108, v109
	v_max3_f32 v66, v66, v110, v111
	v_mfma_f32_32x32x16_bf16 v[2:17], v[90:93], v[230:233], v[2:17]
	v_max3_f32 v66, v66, v112, v113
	v_mov_b32_e32 v67, v66
	s_nop 1
	v_permlane32_swap_b32_e32 v66, v67
	v_max_f32_e32 v67, v67, v67
	v_max_f32_e32 v66, v66, v66
	v_max_f32_e32 v66, v66, v67
	v_sub_f32_e32 v67, v66, v193
	v_cmp_ge_f32_e32 vcc, s91, v67
	v_max_f32_e32 v67, v193, v193
	v_max_f32_e32 v66, v67, v66
	v_mfma_f32_32x32x16_bf16 v[2:17], v[94:97], v[234:237], v[2:17]
	v_sub_f32_e32 v67, v193, v66
	v_mul_f32_e32 v67, 0x3e0293ee, v67
	v_exp_f32_e32 v67, v67
	s_cmp_eq_u64 vcc, exec
	s_waitcnt lgkmcnt(0)
	s_waitcnt vmcnt(0)
	s_barrier
	s_cselect_b64 s[38:39], -1, 0
	s_waitcnt vmcnt(0)
	v_cndmask_b32_e64 v197, v67, 1.0, s[38:39]
	v_cmp_gt_f32_e32 vcc, 1.0, v197
	s_lshl_b32 s42, s21, 11
	s_add_i32 m0, s42, 0x4000
	s_nop 0
	global_load_lds_dwordx4 v88, s[100:101]
	s_add_i32 m0, s42, 0x4400
	s_nop 0
	global_load_lds_dwordx4 v89, s[100:101]
	s_cbranch_vccz .LBB0_582
	s_and_saveexec_b64 s[40:41], s[0:1]
	ds_write_b32 v177, v197 offset:128
	s_or_b64 exec, exec, s[40:41]
	s_waitcnt lgkmcnt(0)
	v_add_u32_e32 v67, s70, v164
	ds_read_b128 v[68:71], v67 offset:224
	ds_read_b128 v[72:75], v67 offset:192
	ds_read_b128 v[76:79], v67 offset:128
	ds_read_b128 v[80:83], v67 offset:160
	s_waitcnt lgkmcnt(3)
	v_pk_mul_f32 v[64:65], v[64:65], v[70:71]
	v_pk_mul_f32 v[62:63], v[62:63], v[68:69]
	s_waitcnt lgkmcnt(2)
	v_pk_mul_f32 v[60:61], v[60:61], v[74:75]
	v_pk_mul_f32 v[58:59], v[58:59], v[72:73]
	s_waitcnt lgkmcnt(0)
	v_pk_mul_f32 v[56:57], v[56:57], v[82:83]
	v_pk_mul_f32 v[54:55], v[54:55], v[80:81]
	v_pk_mul_f32 v[52:53], v[52:53], v[78:79]
	v_pk_mul_f32 v[50:51], v[50:51], v[76:77]
	v_pk_mul_f32 v[48:49], v[48:49], v[70:71]
	v_pk_mul_f32 v[46:47], v[46:47], v[68:69]
	v_pk_mul_f32 v[44:45], v[44:45], v[74:75]
	v_pk_mul_f32 v[42:43], v[42:43], v[72:73]
	v_pk_mul_f32 v[40:41], v[40:41], v[82:83]
	v_pk_mul_f32 v[38:39], v[38:39], v[80:81]
	v_pk_mul_f32 v[36:37], v[36:37], v[78:79]
	v_pk_mul_f32 v[34:35], v[34:35], v[76:77]
	v_pk_mul_f32 v[32:33], v[32:33], v[70:71]
	v_pk_mul_f32 v[30:31], v[30:31], v[68:69]
	v_pk_mul_f32 v[28:29], v[28:29], v[74:75]
	v_pk_mul_f32 v[26:27], v[26:27], v[72:73]
	v_pk_mul_f32 v[24:25], v[24:25], v[82:83]
	v_pk_mul_f32 v[22:23], v[22:23], v[80:81]
	v_pk_mul_f32 v[20:21], v[20:21], v[78:79]
	v_pk_mul_f32 v[18:19], v[18:19], v[76:77]
	v_pk_mul_f32 v[16:17], v[16:17], v[70:71]
	v_pk_mul_f32 v[14:15], v[14:15], v[68:69]
	v_pk_mul_f32 v[12:13], v[12:13], v[74:75]
	v_pk_mul_f32 v[10:11], v[10:11], v[72:73]
	v_pk_mul_f32 v[8:9], v[8:9], v[82:83]
	v_pk_mul_f32 v[6:7], v[6:7], v[80:81]
	v_pk_mul_f32 v[4:5], v[4:5], v[78:79]
	v_pk_mul_f32 v[2:3], v[2:3], v[76:77]
.LBB0_582:
	v_cndmask_b32_e64 v193, v66, v193, s[38:39]
	v_mul_f32_e32 v66, 0xbe0293ee, v193
	s_addk_i32 s71, 0xff80
	v_fmamk_f32 v67, v114, 0x3e0293ee, v66
	v_fmamk_f32 v68, v115, 0x3e0293ee, v66
	v_fmamk_f32 v69, v116, 0x3e0293ee, v66
	v_fmamk_f32 v70, v117, 0x3e0293ee, v66
	v_fmamk_f32 v71, v118, 0x3e0293ee, v66
	v_fmamk_f32 v72, v119, 0x3e0293ee, v66
	v_fmamk_f32 v73, v120, 0x3e0293ee, v66
	v_fmamk_f32 v74, v121, 0x3e0293ee, v66
	v_fmamk_f32 v75, v122, 0x3e0293ee, v66
	v_fmamk_f32 v76, v123, 0x3e0293ee, v66
	v_fmamk_f32 v77, v124, 0x3e0293ee, v66
	v_fmamk_f32 v78, v125, 0x3e0293ee, v66
	v_fmamk_f32 v79, v126, 0x3e0293ee, v66
	v_fmamk_f32 v80, v127, 0x3e0293ee, v66
	v_fmamk_f32 v81, v128, 0x3e0293ee, v66
	v_fmamk_f32 v82, v129, 0x3e0293ee, v66
	s_add_u32 s50, s50, s73
	v_exp_f32_e32 v127, v67
	v_exp_f32_e32 v129, v68
	v_exp_f32_e32 v125, v69
	v_exp_f32_e32 v128, v70
	v_exp_f32_e32 v123, v71
	v_exp_f32_e32 v126, v72
	v_exp_f32_e32 v122, v73
	v_exp_f32_e32 v124, v74
	v_exp_f32_e32 v119, v75
	v_exp_f32_e32 v121, v76
	v_exp_f32_e32 v117, v77
	v_exp_f32_e32 v120, v78
	v_exp_f32_e32 v115, v79
	v_exp_f32_e32 v118, v80
	v_exp_f32_e32 v114, v81
	v_exp_f32_e32 v116, v82
	s_addc_u32 s51, s51, 0
	v_pk_fma_f32 v[112:113], v[112:113], s[90:91], v[66:67] op_sel_hi:[1,0,0]
	v_pk_fma_f32 v[110:111], v[110:111], s[90:91], v[66:67] op_sel_hi:[1,0,0]
	v_pk_fma_f32 v[108:109], v[108:109], s[90:91], v[66:67] op_sel_hi:[1,0,0]
	v_pk_fma_f32 v[106:107], v[106:107], s[90:91], v[66:67] op_sel_hi:[1,0,0]
	v_pk_fma_f32 v[104:105], v[104:105], s[90:91], v[66:67] op_sel_hi:[1,0,0]
	v_pk_fma_f32 v[102:103], v[102:103], s[90:91], v[66:67] op_sel_hi:[1,0,0]
	v_pk_fma_f32 v[100:101], v[100:101], s[90:91], v[66:67] op_sel_hi:[1,0,0]
	v_pk_fma_f32 v[98:99], v[98:99], s[90:91], v[66:67] op_sel_hi:[1,0,0]
	v_add_f32_e32 v66, v198, v199
	s_waitcnt lgkmcnt(0)
	s_add_u32 s96, s96, s73
	v_fmac_f32_e32 v66, v194, v178
	v_add_f32_e32 v178, v209, v210
	s_addc_u32 s97, s97, 0
	s_add_i32 s38, s44, 1
	v_fmac_f32_e32 v178, v66, v208
	s_cmp_ge_i32 s38, s68
	v_add_u32_e32 v196, 0xffffff80, v196
	s_cbranch_scc1 .LBB0_585
	s_mov_b32 s75, s44
	v_mov_b32_e32 v194, v197
	s_branch .LBB0_560

.LBB0_589:
	v_exp_f32_e32 v130, v98
	v_add_f32_e32 v98, 0, v127
	v_add_f32_e32 v98, v129, v98
	v_add_f32_e32 v98, v125, v98
	v_add_f32_e32 v98, v128, v98
	v_add_f32_e32 v98, v123, v98
	v_add_f32_e32 v98, v126, v98
	v_add_f32_e32 v98, v122, v98
	v_add_f32_e32 v98, v124, v98
	v_add_f32_e32 v98, v119, v98
	v_add_f32_e32 v98, v121, v98
	v_add_f32_e32 v98, v117, v98
	v_add_f32_e32 v98, v120, v98
	v_add_f32_e32 v98, v115, v98
	v_exp_f32_e32 v132, v99
	v_add_f32_e32 v98, v118, v98
	v_exp_f32_e32 v133, v100
	v_add_f32_e32 v98, v114, v98
	v_exp_f32_e32 v134, v101
	v_add_f32_e32 v98, v116, v98
	v_exp_f32_e32 v135, v102
	v_add_f32_e32 v98, v130, v98
	v_exp_f32_e32 v136, v103
	v_add_f32_e32 v98, v132, v98
	v_exp_f32_e32 v137, v104
	v_add_f32_e32 v98, v133, v98
	v_exp_f32_e32 v138, v105
	v_add_f32_e32 v98, v134, v98
	v_exp_f32_e32 v139, v106
	v_add_f32_e32 v98, v135, v98
	v_exp_f32_e32 v140, v107
	v_add_f32_e32 v98, v136, v98
	v_exp_f32_e32 v141, v108
	v_add_f32_e32 v98, v137, v98
	v_exp_f32_e32 v142, v109
	v_add_f32_e32 v98, v138, v98
	v_exp_f32_e32 v143, v110
	v_add_f32_e32 v98, v139, v98
	v_exp_f32_e32 v144, v111
	v_add_f32_e32 v98, v140, v98
	v_exp_f32_e32 v145, v112
	v_add_f32_e32 v98, v141, v98
	v_exp_f32_e32 v146, v113
	v_add_f32_e32 v98, v142, v98
	v_add_f32_e32 v98, v143, v98
	v_add_f32_e32 v98, v144, v98
	v_add_f32_e32 v98, v145, v98
	v_add_f32_e32 v98, v146, v98
	v_mov_b32_e32 v99, v98
	v_cvt_pk_bf16_f32 v100, v127, v129
	v_cvt_pk_bf16_f32 v101, v125, v128
	v_cvt_pk_bf16_f32 v102, v123, v126
	v_cvt_pk_bf16_f32 v103, v122, v124
	s_nop 1
	v_permlane32_swap_b32_e32 v98, v99
	v_permlane32_swap_b32_e32 v100, v102
	v_permlane32_swap_b32_e32 v101, v103
	v_cvt_pk_bf16_f32 v104, v119, v121
	v_cvt_pk_bf16_f32 v105, v117, v120
	v_cvt_pk_bf16_f32 v106, v115, v118
	v_cvt_pk_bf16_f32 v107, v114, v116
	v_cvt_pk_bf16_f32 v108, v130, v132
	v_cvt_pk_bf16_f32 v109, v133, v134
	v_cvt_pk_bf16_f32 v110, v135, v136
	v_cvt_pk_bf16_f32 v111, v137, v138
	v_cvt_pk_bf16_f32 v112, v139, v140
	v_cvt_pk_bf16_f32 v113, v141, v142
	v_cvt_pk_bf16_f32 v114, v143, v144
	v_cvt_pk_bf16_f32 v115, v145, v146
	s_nop 0
	v_permlane32_swap_b32_e32 v104, v106
	v_permlane32_swap_b32_e32 v105, v107
	v_permlane32_swap_b32_e32 v108, v110
	v_permlane32_swap_b32_e32 v109, v111
	v_permlane32_swap_b32_e32 v112, v114
	v_permlane32_swap_b32_e32 v113, v115
	ds_read_b64_tr_b16 v[116:117], v176 offset:0
	ds_read_b64_tr_b16 v[118:119], v176 offset:0x800
	ds_read_b64_tr_b16 v[120:121], v176 offset:0x1000
	ds_read_b64_tr_b16 v[122:123], v176 offset:0x1800
	ds_read_b64_tr_b16 v[124:125], v176 offset:0x2000
	ds_read_b64_tr_b16 v[126:127], v176 offset:0x2800
	ds_read_b64_tr_b16 v[132:133], v176 offset:0x3000
	ds_read_b64_tr_b16 v[134:135], v176 offset:0x3800
	s_waitcnt lgkmcnt(0)
	s_nop 0
	v_mfma_f32_32x32x16_bf16 v[50:65], v[100:103], v[116:119], v[50:65]
	ds_read_b64_tr_b16 v[116:117], v176 offset:0x200
	ds_read_b64_tr_b16 v[118:119], v176 offset:0xa00
	v_mfma_f32_32x32x16_bf16 v[50:65], v[104:107], v[120:123], v[50:65]
	ds_read_b64_tr_b16 v[120:121], v176 offset:0x1200
	ds_read_b64_tr_b16 v[122:123], v176 offset:0x1a00
	v_mfma_f32_32x32x16_bf16 v[50:65], v[108:111], v[124:127], v[50:65]
	ds_read_b64_tr_b16 v[124:125], v176 offset:0x2200
	ds_read_b64_tr_b16 v[126:127], v176 offset:0x2a00
	v_mfma_f32_32x32x16_bf16 v[50:65], v[112:115], v[132:135], v[50:65]
	ds_read_b64_tr_b16 v[132:133], v176 offset:0x3200
	ds_read_b64_tr_b16 v[134:135], v176 offset:0x3a00
	s_waitcnt lgkmcnt(0)
	v_mfma_f32_32x32x16_bf16 v[34:49], v[100:103], v[116:119], v[34:49]
	ds_read_b64_tr_b16 v[116:117], v176 offset:0x400
	ds_read_b64_tr_b16 v[118:119], v176 offset:0xc00
	v_mfma_f32_32x32x16_bf16 v[34:49], v[104:107], v[120:123], v[34:49]
	ds_read_b64_tr_b16 v[120:121], v176 offset:0x1400
	ds_read_b64_tr_b16 v[122:123], v176 offset:0x1c00
	v_mfma_f32_32x32x16_bf16 v[34:49], v[108:111], v[124:127], v[34:49]
	ds_read_b64_tr_b16 v[124:125], v176 offset:0x2400
	ds_read_b64_tr_b16 v[126:127], v176 offset:0x2c00
	v_mfma_f32_32x32x16_bf16 v[34:49], v[112:115], v[132:135], v[34:49]
	ds_read_b64_tr_b16 v[132:133], v176 offset:0x3400
	ds_read_b64_tr_b16 v[134:135], v176 offset:0x3c00
	s_waitcnt lgkmcnt(0)
	v_mfma_f32_32x32x16_bf16 v[18:33], v[100:103], v[116:119], v[18:33]
	ds_read_b64_tr_b16 v[116:117], v176 offset:0x600
	ds_read_b64_tr_b16 v[118:119], v176 offset:0xe00
	v_mfma_f32_32x32x16_bf16 v[18:33], v[104:107], v[120:123], v[18:33]
	ds_read_b64_tr_b16 v[120:121], v176 offset:0x1600
	ds_read_b64_tr_b16 v[122:123], v176 offset:0x1e00
	v_mfma_f32_32x32x16_bf16 v[18:33], v[108:111], v[124:127], v[18:33]
	ds_read_b64_tr_b16 v[124:125], v176 offset:0x2600
	ds_read_b64_tr_b16 v[126:127], v176 offset:0x2e00
	v_mfma_f32_32x32x16_bf16 v[18:33], v[112:115], v[132:135], v[18:33]
	ds_read_b64_tr_b16 v[132:133], v176 offset:0x3600
	ds_read_b64_tr_b16 v[134:135], v176 offset:0x3e00
	s_waitcnt lgkmcnt(0)
	v_mfma_f32_32x32x16_bf16 v[2:17], v[100:103], v[116:119], v[2:17]
	v_max_f32_e32 v100, v83, v83
	v_max_f32_e32 v101, v82, v82
	v_max_f32_e32 v100, v101, v100
	v_max3_f32 v100, v100, v84, v85
	v_max3_f32 v100, v100, v86, v87
	v_max3_f32 v100, v100, v88, v89
	v_max3_f32 v100, v100, v90, v91
	v_max3_f32 v100, v100, v92, v93
	v_max3_f32 v100, v100, v94, v95
	v_mfma_f32_32x32x16_bf16 v[2:17], v[104:107], v[120:123], v[2:17]
	v_max3_f32 v100, v100, v96, v97
	v_max3_f32 v100, v100, v66, v67
	v_max3_f32 v100, v100, v68, v69
	v_max3_f32 v100, v100, v70, v71
	v_max3_f32 v100, v100, v72, v73
	v_max3_f32 v100, v100, v74, v75
	v_max3_f32 v100, v100, v76, v77
	v_max3_f32 v100, v100, v78, v79
	v_mfma_f32_32x32x16_bf16 v[2:17], v[108:111], v[124:127], v[2:17]
	v_max3_f32 v100, v100, v80, v81
	v_mov_b32_e32 v101, v100
	s_nop 1
	v_permlane32_swap_b32_e32 v100, v101
	v_max_f32_e32 v101, v101, v101
	v_max_f32_e32 v100, v100, v100
	v_max_f32_e32 v100, v100, v101
	v_sub_f32_e32 v101, v100, v193
	v_cmp_ge_f32_e32 vcc, s91, v101
	v_max_f32_e32 v101, v193, v193
	v_max_f32_e32 v101, v101, v100
	v_mfma_f32_32x32x16_bf16 v[2:17], v[112:115], v[132:135], v[2:17]
	v_sub_f32_e32 v100, v193, v101
	v_mul_f32_e32 v100, 0x3e0293ee, v100
	v_exp_f32_e32 v100, v100
	s_cmp_eq_u64 vcc, exec
	s_cselect_b64 s[0:1], -1, 0
	s_waitcnt lgkmcnt(0)
	s_waitcnt vmcnt(0)
	s_barrier
	v_cndmask_b32_e64 v100, v100, 1.0, s[0:1]
	v_cmp_gt_f32_e32 vcc, 1.0, v100
	s_cbranch_vccz .LBB0_593
	v_cmp_gt_u32_e32 vcc, 32, v165
	s_and_saveexec_b64 s[12:13], vcc
	ds_write_b32 v177, v100 offset:128
	s_or_b64 exec, exec, s[12:13]
	s_waitcnt lgkmcnt(0)
	v_add_u32_e32 v114, s70, v164
	ds_read_b128 v[102:105], v114 offset:224
	ds_read_b128 v[106:109], v114 offset:192
	ds_read_b128 v[110:113], v114 offset:160
	ds_read_b128 v[114:117], v114 offset:128
	s_waitcnt lgkmcnt(3)
	v_pk_mul_f32 v[62:63], v[62:63], v[102:103]
	s_waitcnt lgkmcnt(2)
	v_pk_mul_f32 v[58:59], v[58:59], v[106:107]
	s_waitcnt lgkmcnt(1)
	v_pk_mul_f32 v[54:55], v[54:55], v[110:111]
	v_pk_mul_f32 v[64:65], v[64:65], v[104:105]
	v_pk_mul_f32 v[60:61], v[60:61], v[108:109]
	v_pk_mul_f32 v[56:57], v[56:57], v[112:113]
	s_waitcnt lgkmcnt(0)
	v_pk_mul_f32 v[52:53], v[52:53], v[116:117]
	v_pk_mul_f32 v[50:51], v[50:51], v[114:115]
	v_pk_mul_f32 v[46:47], v[46:47], v[102:103]
	v_pk_mul_f32 v[42:43], v[42:43], v[106:107]
	v_pk_mul_f32 v[38:39], v[38:39], v[110:111]
	v_pk_mul_f32 v[48:49], v[48:49], v[104:105]
	v_pk_mul_f32 v[44:45], v[44:45], v[108:109]
	v_pk_mul_f32 v[40:41], v[40:41], v[112:113]
	v_pk_mul_f32 v[36:37], v[36:37], v[116:117]
	v_pk_mul_f32 v[34:35], v[34:35], v[114:115]
	v_pk_mul_f32 v[30:31], v[30:31], v[102:103]
	v_pk_mul_f32 v[26:27], v[26:27], v[106:107]
	v_pk_mul_f32 v[22:23], v[22:23], v[110:111]
	v_pk_mul_f32 v[32:33], v[32:33], v[104:105]
	v_pk_mul_f32 v[28:29], v[28:29], v[108:109]
	v_pk_mul_f32 v[24:25], v[24:25], v[112:113]
	v_pk_mul_f32 v[20:21], v[20:21], v[116:117]
	v_pk_mul_f32 v[18:19], v[18:19], v[114:115]
	v_pk_mul_f32 v[14:15], v[14:15], v[102:103]
	v_pk_mul_f32 v[10:11], v[10:11], v[106:107]
	v_pk_mul_f32 v[6:7], v[6:7], v[110:111]
	v_pk_mul_f32 v[16:17], v[16:17], v[104:105]
	v_pk_mul_f32 v[12:13], v[12:13], v[108:109]
	v_pk_mul_f32 v[8:9], v[8:9], v[112:113]
	v_pk_mul_f32 v[4:5], v[4:5], v[116:117]
	v_pk_mul_f32 v[2:3], v[2:3], v[114:115]
